# PH5 GEMM loop converted to SGPR-base LDS-DMA addressing with v_mad_u32_u24 row offsets (replaces 4 v_mul_lo_u32 + 24 v_lshl_add_u64 per K iteration)
# speedup vs baseline: 1.0118x; 1.0003x over previous
; #define PG8_STAGE(bufoff, gbase, RR, ld) do { _Pragma("unroll") for (int _i = 0; _i < 2; ++_i) \
;         __builtin_amdgcn_global_load_lds((const unsigned*)((const char*)(gbase) + (RR)[_i] * (ld) + C2[_i]), (LAS unsigned*)(lds + (bufoff) + ldsw + _i * 8192), 16, 0, 0); } while (0)
; #define PG8_LDA(dst, b, h) do { _Pragma("unroll") for (int m = 0; m < 4; ++m) _Pragma("unroll") for (int k = 0; k < 2; ++k) dst[m][k] = *(const LAS bf16x8*)(lds + PG8_SA(b, h) + aoff + m * 2048 + k * 1024); } while (0)
; #define PG8_LDB(dst, b, h) do { _Pragma("unroll") for (int n = 0; n < 2; ++n) _Pragma("unroll") for (int k = 0; k < 2; ++k) dst[n][k] = *(const LAS bf16x8*)(lds + PG8_SB(b, h) + boff + n * 2048 + k * 1024); } while (0)
; #define PG8_WAIT_V(n) asm volatile("s_waitcnt vmcnt(" #n ")" ::: "memory")
; #define PG8_WAIT_L(n) asm volatile("s_waitcnt lgkmcnt(" #n ")" ::: "memory")
; #define PG8_BAR __builtin_amdgcn_s_barrier()
; #define PG8_SCHED __builtin_amdgcn_sched_barrier(0)
; template <class Sched, class Epi>
; __device__ __forceinline__ void gemm_run(LAS unsigned char* lds, const Sched& S, const Epi& E) {
;     ...
;     for (;;) {
;         const bool has_next = S.next(ui + 1, nxt);
;         const char* nA = has_next ? nxt.A : cA; const char* nB = has_next ? nxt.B : cB; const unsigned nlda = has_next ? nxt.lda : lda, nldb = has_next ? nxt.ldb : ldb;
;         const int nt = cur.nt;
;         for (int t = 0; t < nt; t += 2) {
;             const bool last = (t == nt - 2);
;             const char* a1 = cA + (size_t)(t + 1) * kstep;
;             const char* a2 = last ? nA : cA + (size_t)(t + 2) * kstep; const char* b2 = last ? nB : cB + (size_t)(t + 2) * kstep;
;             const unsigned la2 = last ? nlda : lda, lb2 = last ? nldb : ldb;
;             const char* a3 = a2 + kstep; const char* b3 = b2 + kstep;
;             PG8_LDB(B0, 0, 0); PG8_LDB(B1, 0, 1); PG8_SCHED; PG8_LDA(At, 0, 0); PG8_STAGE(PG8_SA(1, 1), a1 + (size_t)HALF * lda, RA, lda);
;             PG8_WAIT_V(8); PG8_WAIT_L(0); PG8_BAR; PG8_MMA(0, 0, At, B0); PG8_MMA(0, 1, At, B1); PG8_BAR; PG8_SCHED;
;             PG8_LDA(At, 0, 1); PG8_STAGE(PG8_SB(0, 0), b2, RB, lb2); PG8_STAGE(PG8_SB(0, 1), b2 + (size_t)HALF * lb2, RB, lb2); PG8_STAGE(PG8_SA(0, 0), a2, RA, la2);
;             PG8_WAIT_V(8); PG8_WAIT_L(0); PG8_BAR; PG8_MMA(1, 0, At, B0); PG8_MMA(1, 1, At, B1); PG8_BAR; PG8_SCHED;
.LBB0_805:
	s_mov_b32 s57, s7
	s_lshl_b64 s[48:49], s[56:57], 7
	v_mad_u32_u24 v224, v191, s56, v150
	v_mad_u32_u24 v226, v192, s56, v150
	v_add_u32_e32 v224, s48, v224
	v_add_u32_e32 v226, s48, v226
	v_mul_lo_u32 v148, v191, s56
	v_lshl_add_u64 v[2:3], s[54:55], 0, v[150:151]
	v_lshl_add_u64 v[4:5], s[48:49], 0, v[148:149]
	v_mul_lo_u32 v148, v192, s56
	s_add_i32 s44, s81, -2
	v_lshl_add_u64 v[130:131], v[2:3], 0, v[4:5]
	v_lshl_add_u64 v[4:5], s[48:49], 0, v[148:149]
	s_add_u32 s45, s58, 0x100
	v_lshl_add_u64 v[132:133], v[2:3], 0, v[4:5]
	s_addc_u32 s46, s59, 0
	s_mov_b32 s6, 0
	s_mov_b64 s[58:59], 0
	ds_read_b128 v[134:137], v193
	ds_read_b128 v[138:141], v193 offset:1024
	ds_read_b128 v[142:145], v193 offset:2048
	ds_read_b128 v[152:155], v193 offset:3072
	ds_read_b128 v[156:159], v194
	ds_read_b128 v[160:163], v194 offset:1024
	ds_read_b128 v[164:167], v194 offset:2048
	ds_read_b128 v[168:171], v194 offset:3072
	s_add_i32 s47, s6, 2
	s_add_u32 s48, s54, s58
	s_addc_u32 s49, s55, s59
	s_mov_b32 s98, s48
	s_mov_b32 s99, s49
	s_add_u32 s48, s48, 0x100
	s_addc_u32 s49, s49, 0
	s_add_u32 s50, s45, s58
	s_addc_u32 s51, s46, s59
	s_cmp_eq_u32 s44, s6
	s_cselect_b32 s6, s39, s82
	s_cselect_b32 s61, s31, s49
	s_cselect_b32 s60, s30, s48
	s_cselect_b32 s62, s80, s56
	s_cselect_b32 s49, s41, s51
	s_cselect_b32 s48, s40, s50
	s_add_i32 m0, s43, 0xc000
	ds_read_b128 v[172:175], v195
	ds_read_b128 v[176:179], v195 offset:1024
	ds_read_b128 v[180:183], v195 offset:2048
	ds_read_b128 v[196:199], v195 offset:3072
	ds_read_b128 v[200:203], v195 offset:4096
	ds_read_b128 v[204:207], v195 offset:5120
	ds_read_b128 v[208:211], v195 offset:6144
	ds_read_b128 v[212:215], v195 offset:7168
	global_load_lds_dwordx4 v224, s[98:99]
	s_add_i32 m0, s43, 0xe000
	s_nop 0
	global_load_lds_dwordx4 v226, s[98:99]
	s_waitcnt vmcnt(8)
	s_waitcnt lgkmcnt(0)
	s_barrier
	s_waitcnt lgkmcnt(0)
	v_mfma_f32_16x16x32_bf16 v[126:129], v[134:137], v[172:175], 0
	v_mfma_f32_16x16x32_bf16 v[118:121], v[142:145], v[172:175], 0
	v_mfma_f32_16x16x32_bf16 v[110:113], v[134:137], v[180:183], 0
	v_mfma_f32_16x16x32_bf16 v[102:105], v[142:145], v[180:183], 0
	v_mfma_f32_16x16x32_bf16 v[94:97], v[134:137], v[200:203], 0
	v_mfma_f32_16x16x32_bf16 v[86:89], v[142:145], v[200:203], 0
	v_mfma_f32_16x16x32_bf16 v[78:81], v[134:137], v[208:211], 0
	v_mfma_f32_16x16x32_bf16 v[70:73], v[142:145], v[208:211], 0
	v_mfma_f32_16x16x32_bf16 v[126:129], v[138:141], v[176:179], v[126:129]
	v_mfma_f32_16x16x32_bf16 v[118:121], v[152:155], v[176:179], v[118:121]
	v_mfma_f32_16x16x32_bf16 v[110:113], v[138:141], v[196:199], v[110:113]
	v_mfma_f32_16x16x32_bf16 v[102:105], v[152:155], v[196:199], v[102:105]
	v_mfma_f32_16x16x32_bf16 v[94:97], v[138:141], v[204:207], v[94:97]
	v_mfma_f32_16x16x32_bf16 v[86:89], v[152:155], v[204:207], v[86:89]
	v_mfma_f32_16x16x32_bf16 v[78:81], v[138:141], v[212:215], v[78:81]
	v_mfma_f32_16x16x32_bf16 v[70:73], v[152:155], v[212:215], v[70:73]
	v_mfma_f32_16x16x32_bf16 v[122:125], v[156:159], v[172:175], 0
	v_mfma_f32_16x16x32_bf16 v[114:117], v[164:167], v[172:175], 0
	v_mfma_f32_16x16x32_bf16 v[106:109], v[156:159], v[180:183], 0
	v_mfma_f32_16x16x32_bf16 v[98:101], v[164:167], v[180:183], 0
	v_mfma_f32_16x16x32_bf16 v[90:93], v[156:159], v[200:203], 0
	v_mfma_f32_16x16x32_bf16 v[82:85], v[164:167], v[200:203], 0
	v_mfma_f32_16x16x32_bf16 v[74:77], v[156:159], v[208:211], 0
	v_mfma_f32_16x16x32_bf16 v[66:69], v[164:167], v[208:211], 0
	v_mfma_f32_16x16x32_bf16 v[122:125], v[160:163], v[176:179], v[122:125]
	v_mfma_f32_16x16x32_bf16 v[114:117], v[168:171], v[176:179], v[114:117]
	v_mfma_f32_16x16x32_bf16 v[106:109], v[160:163], v[196:199], v[106:109]
	v_mfma_f32_16x16x32_bf16 v[98:101], v[168:171], v[196:199], v[98:101]
	v_mfma_f32_16x16x32_bf16 v[90:93], v[160:163], v[204:207], v[90:93]
	v_mfma_f32_16x16x32_bf16 v[82:85], v[168:171], v[204:207], v[82:85]
	v_mfma_f32_16x16x32_bf16 v[74:77], v[160:163], v[212:215], v[74:77]
	v_mfma_f32_16x16x32_bf16 v[66:69], v[168:171], v[212:215], v[66:69]
	s_barrier
	v_mad_u32_u24 v216, v185, s6, v146
	s_add_i32 s50, s74, s3
	s_mov_b32 m0, s50
	ds_read_b128 v[172:175], v195 offset:16384
	ds_read_b128 v[176:179], v195 offset:17408
	ds_read_b128 v[180:183], v195 offset:18432
	ds_read_b128 v[196:199], v195 offset:19456
	ds_read_b128 v[200:203], v195 offset:20480
	ds_read_b128 v[204:207], v195 offset:21504
	ds_read_b128 v[208:211], v195 offset:22528
	ds_read_b128 v[212:215], v195 offset:23552
	global_load_lds_dwordx4 v216, s[48:49]
	v_mad_u32_u24 v218, v187, s6, v146
	s_add_i32 m0, s50, 0x2000
	s_lshl_b64 s[50:51], s[6:7], 7
	s_mov_b64 s[98:99], s[48:49]
	s_add_u32 s48, s48, s50
	s_addc_u32 s49, s49, s51
	s_mov_b64 s[100:101], s[48:49]
	s_add_i32 s6, s75, s3
	global_load_lds_dwordx4 v218, s[98:99]
	s_mov_b32 m0, s6
	v_mad_u32_u24 v220, v184, s62, v146
	global_load_lds_dwordx4 v216, s[48:49]
	s_add_i32 m0, s6, 0x2000
	v_mad_u32_u24 v222, v186, s62, v146
	global_load_lds_dwordx4 v218, s[48:49]
	s_mov_b32 m0, s43
	s_nop 0
	global_load_lds_dwordx4 v220, s[60:61]
	s_mov_b32 m0, s65
	s_nop 0
	global_load_lds_dwordx4 v222, s[60:61]
	s_waitcnt vmcnt(8)
	s_waitcnt lgkmcnt(0)
	s_barrier
; #define PG8_STAGE(bufoff, gbase, RR, ld) do { _Pragma("unroll") for (int _i = 0; _i < 2; ++_i) \
;         __builtin_amdgcn_global_load_lds((const unsigned*)((const char*)(gbase) + (RR)[_i] * (ld) + C2[_i]), (LAS unsigned*)(lds + (bufoff) + ldsw + _i * 8192), 16, 0, 0); } while (0)
; #define PG8_LDA(dst, b, h) do { _Pragma("unroll") for (int m = 0; m < 4; ++m) _Pragma("unroll") for (int k = 0; k < 2; ++k) dst[m][k] = *(const LAS bf16x8*)(lds + PG8_SA(b, h) + aoff + m * 2048 + k * 1024); } while (0)
; #define PG8_LDB(dst, b, h) do { _Pragma("unroll") for (int n = 0; n < 2; ++n) _Pragma("unroll") for (int k = 0; k < 2; ++k) dst[n][k] = *(const LAS bf16x8*)(lds + PG8_SB(b, h) + boff + n * 2048 + k * 1024); } while (0)
; #define PG8_MMA(ai, bj, At, Bt) do { __builtin_amdgcn_s_setprio(1); _Pragma("unroll") for (int m = 0; m < 4; ++m) _Pragma("unroll") for (int n = 0; n < 2; ++n) _Pragma("unroll") for (int k = 0; k < 2; ++k) \
;         acc[ai][bj][m][n] = __builtin_amdgcn_mfma_f32_16x16x32_bf16(Bt[n][k], At[m][k], acc[ai][bj][m][n], 0, 0, 0); __builtin_amdgcn_s_setprio(0); } while (0)
; #define PG8_WAIT_V(n) asm volatile("s_waitcnt vmcnt(" #n ")" ::: "memory")
; #define PG8_WAIT_L(n) asm volatile("s_waitcnt lgkmcnt(" #n ")" ::: "memory")
; #define PG8_BAR __builtin_amdgcn_s_barrier()
; #define PG8_SCHED __builtin_amdgcn_sched_barrier(0)
; template <class Sched, class Epi>
; __device__ __forceinline__ void gemm_run(LAS unsigned char* lds, const Sched& S, const Epi& E) {
;     ...
;             PG8_WAIT_V(8); PG8_WAIT_L(0); PG8_BAR; PG8_MMA(1, 0, At, B0); PG8_MMA(1, 1, At, B1); PG8_BAR; PG8_SCHED;
;             PG8_LDB(B0, 1, 0); PG8_LDB(B1, 1, 1); PG8_SCHED; PG8_LDA(At, 1, 0); PG8_STAGE(PG8_SA(0, 1), a2 + (size_t)HALF * la2, RA, la2);
;             PG8_WAIT_V(8); PG8_WAIT_L(0); PG8_BAR; PG8_MMA(0, 0, At, B0); PG8_MMA(0, 1, At, B1); PG8_BAR; PG8_SCHED;
;             PG8_LDA(At, 1, 1); PG8_STAGE(PG8_SB(1, 0), b3, RB, lb2); PG8_STAGE(PG8_SB(1, 1), b3 + (size_t)HALF * lb2, RB, lb2); PG8_STAGE(PG8_SA(1, 0), a3, RA, la2);
	s_waitcnt lgkmcnt(0)
	v_mfma_f32_16x16x32_bf16 v[62:65], v[134:137], v[172:175], 0
	v_mfma_f32_16x16x32_bf16 v[54:57], v[142:145], v[172:175], 0
	v_mfma_f32_16x16x32_bf16 v[46:49], v[134:137], v[180:183], 0
	v_mfma_f32_16x16x32_bf16 v[38:41], v[142:145], v[180:183], 0
	v_mfma_f32_16x16x32_bf16 v[30:33], v[134:137], v[200:203], 0
	v_mfma_f32_16x16x32_bf16 v[22:25], v[142:145], v[200:203], 0
	v_mfma_f32_16x16x32_bf16 v[14:17], v[134:137], v[208:211], 0
	v_mfma_f32_16x16x32_bf16 v[6:9], v[142:145], v[208:211], 0
	v_mfma_f32_16x16x32_bf16 v[62:65], v[138:141], v[176:179], v[62:65]
	v_mfma_f32_16x16x32_bf16 v[54:57], v[152:155], v[176:179], v[54:57]
	v_mfma_f32_16x16x32_bf16 v[46:49], v[138:141], v[196:199], v[46:49]
	v_mfma_f32_16x16x32_bf16 v[38:41], v[152:155], v[196:199], v[38:41]
	v_mfma_f32_16x16x32_bf16 v[30:33], v[138:141], v[204:207], v[30:33]
	v_mfma_f32_16x16x32_bf16 v[22:25], v[152:155], v[204:207], v[22:25]
	v_mfma_f32_16x16x32_bf16 v[14:17], v[138:141], v[212:215], v[14:17]
	v_mfma_f32_16x16x32_bf16 v[6:9], v[152:155], v[212:215], v[6:9]
	v_mfma_f32_16x16x32_bf16 v[58:61], v[156:159], v[172:175], 0
	v_mfma_f32_16x16x32_bf16 v[50:53], v[164:167], v[172:175], 0
	v_mfma_f32_16x16x32_bf16 v[42:45], v[156:159], v[180:183], 0
	v_mfma_f32_16x16x32_bf16 v[34:37], v[164:167], v[180:183], 0
	v_mfma_f32_16x16x32_bf16 v[26:29], v[156:159], v[200:203], 0
	v_mfma_f32_16x16x32_bf16 v[18:21], v[164:167], v[200:203], 0
	v_mfma_f32_16x16x32_bf16 v[10:13], v[156:159], v[208:211], 0
	v_mfma_f32_16x16x32_bf16 v[2:5], v[164:167], v[208:211], 0
	v_mfma_f32_16x16x32_bf16 v[58:61], v[160:163], v[176:179], v[58:61]
	v_mfma_f32_16x16x32_bf16 v[50:53], v[168:171], v[176:179], v[50:53]
	v_mfma_f32_16x16x32_bf16 v[42:45], v[160:163], v[196:199], v[42:45]
	v_mfma_f32_16x16x32_bf16 v[34:37], v[168:171], v[196:199], v[34:37]
	v_mfma_f32_16x16x32_bf16 v[26:29], v[160:163], v[204:207], v[26:29]
	v_mfma_f32_16x16x32_bf16 v[18:21], v[168:171], v[204:207], v[18:21]
	v_mfma_f32_16x16x32_bf16 v[10:13], v[160:163], v[212:215], v[10:13]
	v_mfma_f32_16x16x32_bf16 v[2:5], v[168:171], v[212:215], v[2:5]
	s_barrier
	s_add_i32 s6, 0, 0x18000
	s_add_i32 s50, 0, 0x1c000
	v_add_u32_e32 v152, s6, v189
	v_add_u32_e32 v168, s50, v189
	ds_read_b128 v[134:137], v152
	ds_read_b128 v[138:141], v152 offset:1024
	ds_read_b128 v[142:145], v152 offset:2048
	ds_read_b128 v[152:155], v152 offset:3072
	ds_read_b128 v[156:159], v168
	ds_read_b128 v[160:163], v168 offset:1024
	ds_read_b128 v[164:167], v168 offset:2048
	ds_read_b128 v[168:171], v168 offset:3072
	s_mov_b32 s63, s7
	s_lshl_b64 s[48:49], s[62:63], 7
	s_add_u32 s48, s60, s48
	s_addc_u32 s49, s61, s49
	s_mov_b32 m0, s66
	ds_read_b128 v[172:175], v195 offset:32768
	ds_read_b128 v[176:179], v195 offset:33792
	ds_read_b128 v[180:183], v195 offset:34816
	ds_read_b128 v[196:199], v195 offset:35840
	ds_read_b128 v[200:203], v195 offset:36864
	ds_read_b128 v[204:207], v195 offset:37888
	ds_read_b128 v[208:211], v195 offset:38912
	ds_read_b128 v[212:215], v195 offset:39936
	global_load_lds_dwordx4 v220, s[48:49]
	s_mov_b32 m0, s67
	s_nop 0
	global_load_lds_dwordx4 v222, s[48:49]
	s_waitcnt vmcnt(8)
	s_waitcnt lgkmcnt(0)
	s_barrier
	s_waitcnt lgkmcnt(0)
	v_mfma_f32_16x16x32_bf16 v[126:129], v[134:137], v[172:175], v[126:129]
	v_mfma_f32_16x16x32_bf16 v[118:121], v[142:145], v[172:175], v[118:121]
	v_mfma_f32_16x16x32_bf16 v[110:113], v[134:137], v[180:183], v[110:113]
	v_mfma_f32_16x16x32_bf16 v[102:105], v[142:145], v[180:183], v[102:105]
	v_mfma_f32_16x16x32_bf16 v[94:97], v[134:137], v[200:203], v[94:97]
	v_mfma_f32_16x16x32_bf16 v[86:89], v[142:145], v[200:203], v[86:89]
	v_mfma_f32_16x16x32_bf16 v[78:81], v[134:137], v[208:211], v[78:81]
	v_mfma_f32_16x16x32_bf16 v[70:73], v[142:145], v[208:211], v[70:73]
	v_mfma_f32_16x16x32_bf16 v[126:129], v[138:141], v[176:179], v[126:129]
	v_mfma_f32_16x16x32_bf16 v[118:121], v[152:155], v[176:179], v[118:121]
	v_mfma_f32_16x16x32_bf16 v[110:113], v[138:141], v[196:199], v[110:113]
	v_mfma_f32_16x16x32_bf16 v[102:105], v[152:155], v[196:199], v[102:105]
	v_mfma_f32_16x16x32_bf16 v[94:97], v[138:141], v[204:207], v[94:97]
	v_mfma_f32_16x16x32_bf16 v[86:89], v[152:155], v[204:207], v[86:89]
	v_mfma_f32_16x16x32_bf16 v[78:81], v[138:141], v[212:215], v[78:81]
	v_mfma_f32_16x16x32_bf16 v[70:73], v[152:155], v[212:215], v[70:73]
	v_mfma_f32_16x16x32_bf16 v[122:125], v[156:159], v[172:175], v[122:125]
	v_mfma_f32_16x16x32_bf16 v[114:117], v[164:167], v[172:175], v[114:117]
	v_mfma_f32_16x16x32_bf16 v[106:109], v[156:159], v[180:183], v[106:109]
	v_mfma_f32_16x16x32_bf16 v[98:101], v[164:167], v[180:183], v[98:101]
	v_mfma_f32_16x16x32_bf16 v[90:93], v[156:159], v[200:203], v[90:93]
	v_mfma_f32_16x16x32_bf16 v[82:85], v[164:167], v[200:203], v[82:85]
	v_mfma_f32_16x16x32_bf16 v[74:77], v[156:159], v[208:211], v[74:77]
	v_mfma_f32_16x16x32_bf16 v[66:69], v[164:167], v[208:211], v[66:69]
	v_mfma_f32_16x16x32_bf16 v[122:125], v[160:163], v[176:179], v[122:125]
	v_mfma_f32_16x16x32_bf16 v[114:117], v[168:171], v[176:179], v[114:117]
	v_mfma_f32_16x16x32_bf16 v[106:109], v[160:163], v[196:199], v[106:109]
	v_mfma_f32_16x16x32_bf16 v[98:101], v[168:171], v[196:199], v[98:101]
	v_mfma_f32_16x16x32_bf16 v[90:93], v[160:163], v[204:207], v[90:93]
	v_mfma_f32_16x16x32_bf16 v[82:85], v[168:171], v[204:207], v[82:85]
	v_mfma_f32_16x16x32_bf16 v[74:77], v[160:163], v[212:215], v[74:77]
	v_mfma_f32_16x16x32_bf16 v[66:69], v[168:171], v[212:215], v[66:69]
	s_barrier
; #define PG8_STAGE(bufoff, gbase, RR, ld) do { _Pragma("unroll") for (int _i = 0; _i < 2; ++_i) \
;         __builtin_amdgcn_global_load_lds((const unsigned*)((const char*)(gbase) + (RR)[_i] * (ld) + C2[_i]), (LAS unsigned*)(lds + (bufoff) + ldsw + _i * 8192), 16, 0, 0); } while (0)
; #define PG8_LDA(dst, b, h) do { _Pragma("unroll") for (int m = 0; m < 4; ++m) _Pragma("unroll") for (int k = 0; k < 2; ++k) dst[m][k] = *(const LAS bf16x8*)(lds + PG8_SA(b, h) + aoff + m * 2048 + k * 1024); } while (0)
; #define PG8_LDB(dst, b, h) do { _Pragma("unroll") for (int n = 0; n < 2; ++n) _Pragma("unroll") for (int k = 0; k < 2; ++k) dst[n][k] = *(const LAS bf16x8*)(lds + PG8_SB(b, h) + boff + n * 2048 + k * 1024); } while (0)
; #define PG8_MMA(ai, bj, At, Bt) do { __builtin_amdgcn_s_setprio(1); _Pragma("unroll") for (int m = 0; m < 4; ++m) _Pragma("unroll") for (int n = 0; n < 2; ++n) _Pragma("unroll") for (int k = 0; k < 2; ++k) \
;         acc[ai][bj][m][n] = __builtin_amdgcn_mfma_f32_16x16x32_bf16(Bt[n][k], At[m][k], acc[ai][bj][m][n], 0, 0, 0); __builtin_amdgcn_s_setprio(0); } while (0)
; #define PG8_WAIT_V(n) asm volatile("s_waitcnt vmcnt(" #n ")" ::: "memory")
; #define PG8_WAIT_L(n) asm volatile("s_waitcnt lgkmcnt(" #n ")" ::: "memory")
; #define PG8_BAR __builtin_amdgcn_s_barrier()
; #define PG8_SCHED __builtin_amdgcn_sched_barrier(0)
; template <class Sched, class Epi>
; __device__ __forceinline__ void gemm_run(LAS unsigned char* lds, const Sched& S, const Epi& E) {
;     ...
;             PG8_LDB(B0, 0, 0); PG8_LDB(B1, 0, 1); PG8_SCHED; PG8_LDA(At, 0, 0); PG8_STAGE(PG8_SA(1, 1), a1 + (size_t)HALF * lda, RA, lda);
;     ...
;             PG8_LDA(At, 1, 1); PG8_STAGE(PG8_SB(1, 0), b3, RB, lb2); PG8_STAGE(PG8_SB(1, 1), b3 + (size_t)HALF * lb2, RB, lb2); PG8_STAGE(PG8_SA(1, 0), a3, RA, la2);
;             PG8_WAIT_V(8); PG8_WAIT_L(0); PG8_BAR; PG8_MMA(1, 0, At, B0); PG8_MMA(1, 1, At, B1); PG8_BAR; PG8_SCHED;
	s_add_i32 s6, s6, s3
	s_add_u32 s98, s98, 0x80
	s_addc_u32 s99, s99, 0
	s_mov_b32 m0, s6
	ds_read_b128 v[172:175], v195 offset:49152
	ds_read_b128 v[176:179], v195 offset:50176
	ds_read_b128 v[180:183], v195 offset:51200
	ds_read_b128 v[196:199], v195 offset:52224
	ds_read_b128 v[200:203], v195 offset:53248
	ds_read_b128 v[204:207], v195 offset:54272
	ds_read_b128 v[208:211], v195 offset:55296
	ds_read_b128 v[212:215], v195 offset:56320
	global_load_lds_dwordx4 v216, s[98:99]
	s_add_i32 m0, s6, 0x2000
	s_add_i32 s6, s50, s3
	global_load_lds_dwordx4 v218, s[98:99]
	s_add_u32 s100, s100, 0x80
	s_addc_u32 s101, s101, 0
	s_mov_b32 m0, s6
	s_nop 0
	global_load_lds_dwordx4 v216, s[100:101]
	s_add_i32 m0, s6, 0x2000
	s_nop 0
	global_load_lds_dwordx4 v218, s[100:101]
	s_add_u32 s48, s60, 0x80
	s_addc_u32 s49, s61, 0
	s_mov_b32 m0, s68
	s_nop 0
	global_load_lds_dwordx4 v220, s[48:49]
	s_mov_b32 m0, s69
	s_nop 0
	global_load_lds_dwordx4 v222, s[48:49]
	s_waitcnt vmcnt(8)
	s_waitcnt lgkmcnt(0)
	s_barrier
	s_waitcnt lgkmcnt(0)
	v_mfma_f32_16x16x32_bf16 v[62:65], v[134:137], v[172:175], v[62:65]
	v_mfma_f32_16x16x32_bf16 v[54:57], v[142:145], v[172:175], v[54:57]
	v_mfma_f32_16x16x32_bf16 v[46:49], v[134:137], v[180:183], v[46:49]
	v_mfma_f32_16x16x32_bf16 v[38:41], v[142:145], v[180:183], v[38:41]
	v_mfma_f32_16x16x32_bf16 v[30:33], v[134:137], v[200:203], v[30:33]
	v_mfma_f32_16x16x32_bf16 v[22:25], v[142:145], v[200:203], v[22:25]
	v_mfma_f32_16x16x32_bf16 v[14:17], v[134:137], v[208:211], v[14:17]
	v_mfma_f32_16x16x32_bf16 v[6:9], v[142:145], v[208:211], v[6:9]
	v_mfma_f32_16x16x32_bf16 v[62:65], v[138:141], v[176:179], v[62:65]
	v_mfma_f32_16x16x32_bf16 v[54:57], v[152:155], v[176:179], v[54:57]
	v_mfma_f32_16x16x32_bf16 v[46:49], v[138:141], v[196:199], v[46:49]
	v_mfma_f32_16x16x32_bf16 v[38:41], v[152:155], v[196:199], v[38:41]
	v_mfma_f32_16x16x32_bf16 v[30:33], v[138:141], v[204:207], v[30:33]
	v_mfma_f32_16x16x32_bf16 v[22:25], v[152:155], v[204:207], v[22:25]
	v_mfma_f32_16x16x32_bf16 v[14:17], v[138:141], v[212:215], v[14:17]
	v_mfma_f32_16x16x32_bf16 v[6:9], v[152:155], v[212:215], v[6:9]
	v_mfma_f32_16x16x32_bf16 v[58:61], v[156:159], v[172:175], v[58:61]
	v_mfma_f32_16x16x32_bf16 v[50:53], v[164:167], v[172:175], v[50:53]
	v_mfma_f32_16x16x32_bf16 v[42:45], v[156:159], v[180:183], v[42:45]
	v_mfma_f32_16x16x32_bf16 v[34:37], v[164:167], v[180:183], v[34:37]
	v_mfma_f32_16x16x32_bf16 v[26:29], v[156:159], v[200:203], v[26:29]
	v_mfma_f32_16x16x32_bf16 v[18:21], v[164:167], v[200:203], v[18:21]
	v_mfma_f32_16x16x32_bf16 v[10:13], v[156:159], v[208:211], v[10:13]
	v_mfma_f32_16x16x32_bf16 v[2:5], v[164:167], v[208:211], v[2:5]
	v_mfma_f32_16x16x32_bf16 v[58:61], v[160:163], v[176:179], v[58:61]
	v_mfma_f32_16x16x32_bf16 v[50:53], v[168:171], v[176:179], v[50:53]
	v_mfma_f32_16x16x32_bf16 v[42:45], v[160:163], v[196:199], v[42:45]
	v_mfma_f32_16x16x32_bf16 v[34:37], v[168:171], v[196:199], v[34:37]
	v_mfma_f32_16x16x32_bf16 v[26:29], v[160:163], v[204:207], v[26:29]
	v_mfma_f32_16x16x32_bf16 v[18:21], v[168:171], v[204:207], v[18:21]
	v_mfma_f32_16x16x32_bf16 v[10:13], v[160:163], v[212:215], v[10:13]
	v_mfma_f32_16x16x32_bf16 v[2:5], v[168:171], v[212:215], v[2:5]
	s_barrier
	s_add_u32 s58, s58, 0x100
	s_addc_u32 s59, s59, 0
	s_cmp_ge_i32 s47, s81
	s_mov_b32 s6, s47
	s_cbranch_scc0 .LBB0_806
	.p2align 6
.LBB0_806:
	ds_read_b128 v[134:137], v193
	ds_read_b128 v[138:141], v193 offset:1024
	ds_read_b128 v[142:145], v193 offset:2048
	ds_read_b128 v[152:155], v193 offset:3072
	ds_read_b128 v[156:159], v194
	ds_read_b128 v[160:163], v194 offset:1024
	ds_read_b128 v[164:167], v194 offset:2048
	ds_read_b128 v[168:171], v194 offset:3072
	s_add_i32 s47, s6, 2
	s_add_u32 s48, s54, s58
	s_addc_u32 s49, s55, s59
	s_mov_b32 s98, s48
	s_mov_b32 s99, s49
	s_add_u32 s48, s48, 0x100
	s_addc_u32 s49, s49, 0
	s_add_u32 s50, s45, s58
	s_addc_u32 s51, s46, s59
	s_cmp_eq_u32 s44, s6
	s_cselect_b32 s6, s39, s82
	s_cselect_b32 s61, s31, s49
	s_cselect_b32 s60, s30, s48
	s_cselect_b32 s62, s80, s56
	s_cselect_b32 s49, s41, s51
	s_cselect_b32 s48, s40, s50
	s_add_i32 m0, s43, 0xc000
	ds_read_b128 v[172:175], v195
	ds_read_b128 v[176:179], v195 offset:1024
	ds_read_b128 v[180:183], v195 offset:2048
	ds_read_b128 v[196:199], v195 offset:3072
	ds_read_b128 v[200:203], v195 offset:4096
	ds_read_b128 v[204:207], v195 offset:5120
	ds_read_b128 v[208:211], v195 offset:6144
	ds_read_b128 v[212:215], v195 offset:7168
	global_load_lds_dwordx4 v224, s[98:99]
	s_add_i32 m0, s43, 0xe000
	s_nop 0
	global_load_lds_dwordx4 v226, s[98:99]
	s_waitcnt vmcnt(8)
	s_waitcnt lgkmcnt(0)
	s_barrier
; #define PG8_STAGE(bufoff, gbase, RR, ld) do { _Pragma("unroll") for (int _i = 0; _i < 2; ++_i) \
;         __builtin_amdgcn_global_load_lds((const unsigned*)((const char*)(gbase) + (RR)[_i] * (ld) + C2[_i]), (LAS unsigned*)(lds + (bufoff) + ldsw + _i * 8192), 16, 0, 0); } while (0)
; #define PG8_LDA(dst, b, h) do { _Pragma("unroll") for (int m = 0; m < 4; ++m) _Pragma("unroll") for (int k = 0; k < 2; ++k) dst[m][k] = *(const LAS bf16x8*)(lds + PG8_SA(b, h) + aoff + m * 2048 + k * 1024); } while (0)
; #define PG8_LDB(dst, b, h) do { _Pragma("unroll") for (int n = 0; n < 2; ++n) _Pragma("unroll") for (int k = 0; k < 2; ++k) dst[n][k] = *(const LAS bf16x8*)(lds + PG8_SB(b, h) + boff + n * 2048 + k * 1024); } while (0)
; #define PG8_MMA(ai, bj, At, Bt) do { __builtin_amdgcn_s_setprio(1); _Pragma("unroll") for (int m = 0; m < 4; ++m) _Pragma("unroll") for (int n = 0; n < 2; ++n) _Pragma("unroll") for (int k = 0; k < 2; ++k) \
;         acc[ai][bj][m][n] = __builtin_amdgcn_mfma_f32_16x16x32_bf16(Bt[n][k], At[m][k], acc[ai][bj][m][n], 0, 0, 0); __builtin_amdgcn_s_setprio(0); } while (0)
; #define PG8_WAIT_V(n) asm volatile("s_waitcnt vmcnt(" #n ")" ::: "memory")
; #define PG8_WAIT_L(n) asm volatile("s_waitcnt lgkmcnt(" #n ")" ::: "memory")
; #define PG8_BAR __builtin_amdgcn_s_barrier()
; #define PG8_SCHED __builtin_amdgcn_sched_barrier(0)
; template <class Sched, class Epi>
; __device__ __forceinline__ void gemm_run(LAS unsigned char* lds, const Sched& S, const Epi& E) {
;     ...
;             PG8_WAIT_V(8); PG8_WAIT_L(0); PG8_BAR; PG8_MMA(0, 0, At, B0); PG8_MMA(0, 1, At, B1); PG8_BAR; PG8_SCHED;
;             PG8_LDA(At, 0, 1); PG8_STAGE(PG8_SB(0, 0), b2, RB, lb2); PG8_STAGE(PG8_SB(0, 1), b2 + (size_t)HALF * lb2, RB, lb2); PG8_STAGE(PG8_SA(0, 0), a2, RA, la2);
;             PG8_WAIT_V(8); PG8_WAIT_L(0); PG8_BAR; PG8_MMA(1, 0, At, B0); PG8_MMA(1, 1, At, B1); PG8_BAR; PG8_SCHED;
;             PG8_LDB(B0, 1, 0); PG8_LDB(B1, 1, 1); PG8_SCHED; PG8_LDA(At, 1, 0); PG8_STAGE(PG8_SA(0, 1), a2 + (size_t)HALF * la2, RA, la2);
	s_waitcnt lgkmcnt(0)
	v_mfma_f32_16x16x32_bf16 v[126:129], v[134:137], v[172:175], v[126:129]
	v_mfma_f32_16x16x32_bf16 v[118:121], v[142:145], v[172:175], v[118:121]
	v_mfma_f32_16x16x32_bf16 v[110:113], v[134:137], v[180:183], v[110:113]
	v_mfma_f32_16x16x32_bf16 v[102:105], v[142:145], v[180:183], v[102:105]
	v_mfma_f32_16x16x32_bf16 v[94:97], v[134:137], v[200:203], v[94:97]
	v_mfma_f32_16x16x32_bf16 v[86:89], v[142:145], v[200:203], v[86:89]
	v_mfma_f32_16x16x32_bf16 v[78:81], v[134:137], v[208:211], v[78:81]
	v_mfma_f32_16x16x32_bf16 v[70:73], v[142:145], v[208:211], v[70:73]
	v_mfma_f32_16x16x32_bf16 v[126:129], v[138:141], v[176:179], v[126:129]
	v_mfma_f32_16x16x32_bf16 v[118:121], v[152:155], v[176:179], v[118:121]
	v_mfma_f32_16x16x32_bf16 v[110:113], v[138:141], v[196:199], v[110:113]
	v_mfma_f32_16x16x32_bf16 v[102:105], v[152:155], v[196:199], v[102:105]
	v_mfma_f32_16x16x32_bf16 v[94:97], v[138:141], v[204:207], v[94:97]
	v_mfma_f32_16x16x32_bf16 v[86:89], v[152:155], v[204:207], v[86:89]
	v_mfma_f32_16x16x32_bf16 v[78:81], v[138:141], v[212:215], v[78:81]
	v_mfma_f32_16x16x32_bf16 v[70:73], v[152:155], v[212:215], v[70:73]
	v_mfma_f32_16x16x32_bf16 v[122:125], v[156:159], v[172:175], v[122:125]
	v_mfma_f32_16x16x32_bf16 v[114:117], v[164:167], v[172:175], v[114:117]
	v_mfma_f32_16x16x32_bf16 v[106:109], v[156:159], v[180:183], v[106:109]
	v_mfma_f32_16x16x32_bf16 v[98:101], v[164:167], v[180:183], v[98:101]
	v_mfma_f32_16x16x32_bf16 v[90:93], v[156:159], v[200:203], v[90:93]
	v_mfma_f32_16x16x32_bf16 v[82:85], v[164:167], v[200:203], v[82:85]
	v_mfma_f32_16x16x32_bf16 v[74:77], v[156:159], v[208:211], v[74:77]
	v_mfma_f32_16x16x32_bf16 v[66:69], v[164:167], v[208:211], v[66:69]
	v_mfma_f32_16x16x32_bf16 v[122:125], v[160:163], v[176:179], v[122:125]
	v_mfma_f32_16x16x32_bf16 v[114:117], v[168:171], v[176:179], v[114:117]
	v_mfma_f32_16x16x32_bf16 v[106:109], v[160:163], v[196:199], v[106:109]
	v_mfma_f32_16x16x32_bf16 v[98:101], v[168:171], v[196:199], v[98:101]
	v_mfma_f32_16x16x32_bf16 v[90:93], v[160:163], v[204:207], v[90:93]
	v_mfma_f32_16x16x32_bf16 v[82:85], v[168:171], v[204:207], v[82:85]
	v_mfma_f32_16x16x32_bf16 v[74:77], v[160:163], v[212:215], v[74:77]
	v_mfma_f32_16x16x32_bf16 v[66:69], v[168:171], v[212:215], v[66:69]
	s_barrier
	v_mad_u32_u24 v216, v185, s6, v146
	s_add_i32 s50, s74, s3
	s_mov_b32 m0, s50
	ds_read_b128 v[172:175], v195 offset:16384
	ds_read_b128 v[176:179], v195 offset:17408
	ds_read_b128 v[180:183], v195 offset:18432
	ds_read_b128 v[196:199], v195 offset:19456
	ds_read_b128 v[200:203], v195 offset:20480
	ds_read_b128 v[204:207], v195 offset:21504
	ds_read_b128 v[208:211], v195 offset:22528
	ds_read_b128 v[212:215], v195 offset:23552
	global_load_lds_dwordx4 v216, s[48:49]
	v_mad_u32_u24 v218, v187, s6, v146
	s_add_i32 m0, s50, 0x2000
	s_lshl_b64 s[50:51], s[6:7], 7
	s_mov_b64 s[98:99], s[48:49]
	s_add_u32 s48, s48, s50
	s_addc_u32 s49, s49, s51
	s_mov_b64 s[100:101], s[48:49]
	s_add_i32 s6, s75, s3
	global_load_lds_dwordx4 v218, s[98:99]
	s_mov_b32 m0, s6
	v_mad_u32_u24 v220, v184, s62, v146
	global_load_lds_dwordx4 v216, s[48:49]
	s_add_i32 m0, s6, 0x2000
	v_mad_u32_u24 v222, v186, s62, v146
	global_load_lds_dwordx4 v218, s[48:49]
	s_mov_b32 m0, s43
	s_nop 0
	global_load_lds_dwordx4 v220, s[60:61]
	s_mov_b32 m0, s65
	s_nop 0
	global_load_lds_dwordx4 v222, s[60:61]
	s_waitcnt vmcnt(8)
	s_waitcnt lgkmcnt(0)
	s_barrier
	s_waitcnt lgkmcnt(0)
	v_mfma_f32_16x16x32_bf16 v[62:65], v[134:137], v[172:175], v[62:65]
	v_mfma_f32_16x16x32_bf16 v[54:57], v[142:145], v[172:175], v[54:57]
	v_mfma_f32_16x16x32_bf16 v[46:49], v[134:137], v[180:183], v[46:49]
	v_mfma_f32_16x16x32_bf16 v[38:41], v[142:145], v[180:183], v[38:41]
	v_mfma_f32_16x16x32_bf16 v[30:33], v[134:137], v[200:203], v[30:33]
	v_mfma_f32_16x16x32_bf16 v[22:25], v[142:145], v[200:203], v[22:25]
	v_mfma_f32_16x16x32_bf16 v[14:17], v[134:137], v[208:211], v[14:17]
	v_mfma_f32_16x16x32_bf16 v[6:9], v[142:145], v[208:211], v[6:9]
	v_mfma_f32_16x16x32_bf16 v[62:65], v[138:141], v[176:179], v[62:65]
	v_mfma_f32_16x16x32_bf16 v[54:57], v[152:155], v[176:179], v[54:57]
	v_mfma_f32_16x16x32_bf16 v[46:49], v[138:141], v[196:199], v[46:49]
	v_mfma_f32_16x16x32_bf16 v[38:41], v[152:155], v[196:199], v[38:41]
	v_mfma_f32_16x16x32_bf16 v[30:33], v[138:141], v[204:207], v[30:33]
	v_mfma_f32_16x16x32_bf16 v[22:25], v[152:155], v[204:207], v[22:25]
	v_mfma_f32_16x16x32_bf16 v[14:17], v[138:141], v[212:215], v[14:17]
	v_mfma_f32_16x16x32_bf16 v[6:9], v[152:155], v[212:215], v[6:9]
	v_mfma_f32_16x16x32_bf16 v[58:61], v[156:159], v[172:175], v[58:61]
	v_mfma_f32_16x16x32_bf16 v[50:53], v[164:167], v[172:175], v[50:53]
	v_mfma_f32_16x16x32_bf16 v[42:45], v[156:159], v[180:183], v[42:45]
	v_mfma_f32_16x16x32_bf16 v[34:37], v[164:167], v[180:183], v[34:37]
	v_mfma_f32_16x16x32_bf16 v[26:29], v[156:159], v[200:203], v[26:29]
	v_mfma_f32_16x16x32_bf16 v[18:21], v[164:167], v[200:203], v[18:21]
	v_mfma_f32_16x16x32_bf16 v[10:13], v[156:159], v[208:211], v[10:13]
	v_mfma_f32_16x16x32_bf16 v[2:5], v[164:167], v[208:211], v[2:5]
	v_mfma_f32_16x16x32_bf16 v[58:61], v[160:163], v[176:179], v[58:61]
	v_mfma_f32_16x16x32_bf16 v[50:53], v[168:171], v[176:179], v[50:53]
	v_mfma_f32_16x16x32_bf16 v[42:45], v[160:163], v[196:199], v[42:45]
	v_mfma_f32_16x16x32_bf16 v[34:37], v[168:171], v[196:199], v[34:37]
	v_mfma_f32_16x16x32_bf16 v[26:29], v[160:163], v[204:207], v[26:29]
	v_mfma_f32_16x16x32_bf16 v[18:21], v[168:171], v[204:207], v[18:21]
	v_mfma_f32_16x16x32_bf16 v[10:13], v[160:163], v[212:215], v[10:13]
	v_mfma_f32_16x16x32_bf16 v[2:5], v[168:171], v[212:215], v[2:5]
	s_barrier
; #define PG8_STAGE(bufoff, gbase, RR, ld) do { _Pragma("unroll") for (int _i = 0; _i < 2; ++_i) \
;         __builtin_amdgcn_global_load_lds((const unsigned*)((const char*)(gbase) + (RR)[_i] * (ld) + C2[_i]), (LAS unsigned*)(lds + (bufoff) + ldsw + _i * 8192), 16, 0, 0); } while (0)
; #define PG8_LDA(dst, b, h) do { _Pragma("unroll") for (int m = 0; m < 4; ++m) _Pragma("unroll") for (int k = 0; k < 2; ++k) dst[m][k] = *(const LAS bf16x8*)(lds + PG8_SA(b, h) + aoff + m * 2048 + k * 1024); } while (0)
; #define PG8_LDB(dst, b, h) do { _Pragma("unroll") for (int n = 0; n < 2; ++n) _Pragma("unroll") for (int k = 0; k < 2; ++k) dst[n][k] = *(const LAS bf16x8*)(lds + PG8_SB(b, h) + boff + n * 2048 + k * 1024); } while (0)
; #define PG8_MMA(ai, bj, At, Bt) do { __builtin_amdgcn_s_setprio(1); _Pragma("unroll") for (int m = 0; m < 4; ++m) _Pragma("unroll") for (int n = 0; n < 2; ++n) _Pragma("unroll") for (int k = 0; k < 2; ++k) \
;         acc[ai][bj][m][n] = __builtin_amdgcn_mfma_f32_16x16x32_bf16(Bt[n][k], At[m][k], acc[ai][bj][m][n], 0, 0, 0); __builtin_amdgcn_s_setprio(0); } while (0)
; #define PG8_WAIT_V(n) asm volatile("s_waitcnt vmcnt(" #n ")" ::: "memory")
; #define PG8_WAIT_L(n) asm volatile("s_waitcnt lgkmcnt(" #n ")" ::: "memory")
; #define PG8_BAR __builtin_amdgcn_s_barrier()
; #define PG8_SCHED __builtin_amdgcn_sched_barrier(0)
; template <class Sched, class Epi>
; __device__ __forceinline__ void gemm_run(LAS unsigned char* lds, const Sched& S, const Epi& E) {
;     ...
;             PG8_LDB(B0, 1, 0); PG8_LDB(B1, 1, 1); PG8_SCHED; PG8_LDA(At, 1, 0); PG8_STAGE(PG8_SA(0, 1), a2 + (size_t)HALF * la2, RA, la2);
;             PG8_WAIT_V(8); PG8_WAIT_L(0); PG8_BAR; PG8_MMA(0, 0, At, B0); PG8_MMA(0, 1, At, B1); PG8_BAR; PG8_SCHED;
;             PG8_LDA(At, 1, 1); PG8_STAGE(PG8_SB(1, 0), b3, RB, lb2); PG8_STAGE(PG8_SB(1, 1), b3 + (size_t)HALF * lb2, RB, lb2); PG8_STAGE(PG8_SA(1, 0), a3, RA, la2);
;             PG8_WAIT_V(8); PG8_WAIT_L(0); PG8_BAR; PG8_MMA(1, 0, At, B0); PG8_MMA(1, 1, At, B1); PG8_BAR; PG8_SCHED;
;         }
;         if (wr == 0) PG8_BAR;
	s_add_i32 s6, 0, 0x18000
	s_add_i32 s50, 0, 0x1c000
	v_add_u32_e32 v152, s6, v189
	v_add_u32_e32 v168, s50, v189
	ds_read_b128 v[134:137], v152
	ds_read_b128 v[138:141], v152 offset:1024
	ds_read_b128 v[142:145], v152 offset:2048
	ds_read_b128 v[152:155], v152 offset:3072
	ds_read_b128 v[156:159], v168
	ds_read_b128 v[160:163], v168 offset:1024
	ds_read_b128 v[164:167], v168 offset:2048
	ds_read_b128 v[168:171], v168 offset:3072
	s_mov_b32 s63, s7
	s_lshl_b64 s[48:49], s[62:63], 7
	s_add_u32 s48, s60, s48
	s_addc_u32 s49, s61, s49
	s_mov_b32 m0, s66
	ds_read_b128 v[172:175], v195 offset:32768
	ds_read_b128 v[176:179], v195 offset:33792
	ds_read_b128 v[180:183], v195 offset:34816
	ds_read_b128 v[196:199], v195 offset:35840
	ds_read_b128 v[200:203], v195 offset:36864
	ds_read_b128 v[204:207], v195 offset:37888
	ds_read_b128 v[208:211], v195 offset:38912
	ds_read_b128 v[212:215], v195 offset:39936
	global_load_lds_dwordx4 v220, s[48:49]
	s_mov_b32 m0, s67
	s_nop 0
	global_load_lds_dwordx4 v222, s[48:49]
	s_waitcnt vmcnt(8)
	s_waitcnt lgkmcnt(0)
	s_barrier
	s_waitcnt lgkmcnt(0)
	v_mfma_f32_16x16x32_bf16 v[126:129], v[134:137], v[172:175], v[126:129]
	v_mfma_f32_16x16x32_bf16 v[118:121], v[142:145], v[172:175], v[118:121]
	v_mfma_f32_16x16x32_bf16 v[110:113], v[134:137], v[180:183], v[110:113]
	v_mfma_f32_16x16x32_bf16 v[102:105], v[142:145], v[180:183], v[102:105]
	v_mfma_f32_16x16x32_bf16 v[94:97], v[134:137], v[200:203], v[94:97]
	v_mfma_f32_16x16x32_bf16 v[86:89], v[142:145], v[200:203], v[86:89]
	v_mfma_f32_16x16x32_bf16 v[78:81], v[134:137], v[208:211], v[78:81]
	v_mfma_f32_16x16x32_bf16 v[70:73], v[142:145], v[208:211], v[70:73]
	v_mfma_f32_16x16x32_bf16 v[126:129], v[138:141], v[176:179], v[126:129]
	v_mfma_f32_16x16x32_bf16 v[118:121], v[152:155], v[176:179], v[118:121]
	v_mfma_f32_16x16x32_bf16 v[110:113], v[138:141], v[196:199], v[110:113]
	v_mfma_f32_16x16x32_bf16 v[102:105], v[152:155], v[196:199], v[102:105]
	v_mfma_f32_16x16x32_bf16 v[94:97], v[138:141], v[204:207], v[94:97]
	v_mfma_f32_16x16x32_bf16 v[86:89], v[152:155], v[204:207], v[86:89]
	v_mfma_f32_16x16x32_bf16 v[78:81], v[138:141], v[212:215], v[78:81]
	v_mfma_f32_16x16x32_bf16 v[70:73], v[152:155], v[212:215], v[70:73]
	v_mfma_f32_16x16x32_bf16 v[122:125], v[156:159], v[172:175], v[122:125]
	v_mfma_f32_16x16x32_bf16 v[114:117], v[164:167], v[172:175], v[114:117]
	v_mfma_f32_16x16x32_bf16 v[106:109], v[156:159], v[180:183], v[106:109]
	v_mfma_f32_16x16x32_bf16 v[98:101], v[164:167], v[180:183], v[98:101]
	v_mfma_f32_16x16x32_bf16 v[90:93], v[156:159], v[200:203], v[90:93]
	v_mfma_f32_16x16x32_bf16 v[82:85], v[164:167], v[200:203], v[82:85]
	v_mfma_f32_16x16x32_bf16 v[74:77], v[156:159], v[208:211], v[74:77]
	v_mfma_f32_16x16x32_bf16 v[66:69], v[164:167], v[208:211], v[66:69]
	v_mfma_f32_16x16x32_bf16 v[122:125], v[160:163], v[176:179], v[122:125]
	v_mfma_f32_16x16x32_bf16 v[114:117], v[168:171], v[176:179], v[114:117]
	v_mfma_f32_16x16x32_bf16 v[106:109], v[160:163], v[196:199], v[106:109]
	v_mfma_f32_16x16x32_bf16 v[98:101], v[168:171], v[196:199], v[98:101]
	v_mfma_f32_16x16x32_bf16 v[90:93], v[160:163], v[204:207], v[90:93]
	v_mfma_f32_16x16x32_bf16 v[82:85], v[168:171], v[204:207], v[82:85]
	v_mfma_f32_16x16x32_bf16 v[74:77], v[160:163], v[212:215], v[74:77]
	v_mfma_f32_16x16x32_bf16 v[66:69], v[168:171], v[212:215], v[66:69]
	s_barrier
	s_add_i32 s6, s6, s3
	s_add_u32 s98, s98, 0x80
	s_addc_u32 s99, s99, 0
	s_mov_b32 m0, s6
	ds_read_b128 v[172:175], v195 offset:49152
	ds_read_b128 v[176:179], v195 offset:50176
	ds_read_b128 v[180:183], v195 offset:51200
	ds_read_b128 v[196:199], v195 offset:52224
	ds_read_b128 v[200:203], v195 offset:53248
	ds_read_b128 v[204:207], v195 offset:54272
	ds_read_b128 v[208:211], v195 offset:55296
	ds_read_b128 v[212:215], v195 offset:56320
	global_load_lds_dwordx4 v216, s[98:99]
	s_add_i32 m0, s6, 0x2000
	s_add_i32 s6, s50, s3
	global_load_lds_dwordx4 v218, s[98:99]
	s_add_u32 s100, s100, 0x80
	s_addc_u32 s101, s101, 0
	s_mov_b32 m0, s6
	s_nop 0
	global_load_lds_dwordx4 v216, s[100:101]
	s_add_i32 m0, s6, 0x2000
	s_nop 0
	global_load_lds_dwordx4 v218, s[100:101]
	s_add_u32 s48, s60, 0x80
	s_addc_u32 s49, s61, 0
	s_mov_b32 m0, s68
	s_nop 0
	global_load_lds_dwordx4 v220, s[48:49]
	s_mov_b32 m0, s69
	s_nop 0
	global_load_lds_dwordx4 v222, s[48:49]
	s_waitcnt vmcnt(8)
	s_waitcnt lgkmcnt(0)
	s_barrier
	s_waitcnt lgkmcnt(0)
	v_mfma_f32_16x16x32_bf16 v[62:65], v[134:137], v[172:175], v[62:65]
	v_mfma_f32_16x16x32_bf16 v[54:57], v[142:145], v[172:175], v[54:57]
	v_mfma_f32_16x16x32_bf16 v[46:49], v[134:137], v[180:183], v[46:49]
	v_mfma_f32_16x16x32_bf16 v[38:41], v[142:145], v[180:183], v[38:41]
	v_mfma_f32_16x16x32_bf16 v[30:33], v[134:137], v[200:203], v[30:33]
	v_mfma_f32_16x16x32_bf16 v[22:25], v[142:145], v[200:203], v[22:25]
	v_mfma_f32_16x16x32_bf16 v[14:17], v[134:137], v[208:211], v[14:17]
	v_mfma_f32_16x16x32_bf16 v[6:9], v[142:145], v[208:211], v[6:9]
	v_mfma_f32_16x16x32_bf16 v[62:65], v[138:141], v[176:179], v[62:65]
	v_mfma_f32_16x16x32_bf16 v[54:57], v[152:155], v[176:179], v[54:57]
	v_mfma_f32_16x16x32_bf16 v[46:49], v[138:141], v[196:199], v[46:49]
	v_mfma_f32_16x16x32_bf16 v[38:41], v[152:155], v[196:199], v[38:41]
	v_mfma_f32_16x16x32_bf16 v[30:33], v[138:141], v[204:207], v[30:33]
	v_mfma_f32_16x16x32_bf16 v[22:25], v[152:155], v[204:207], v[22:25]
	v_mfma_f32_16x16x32_bf16 v[14:17], v[138:141], v[212:215], v[14:17]
	v_mfma_f32_16x16x32_bf16 v[6:9], v[152:155], v[212:215], v[6:9]
	v_mfma_f32_16x16x32_bf16 v[58:61], v[156:159], v[172:175], v[58:61]
	v_mfma_f32_16x16x32_bf16 v[50:53], v[164:167], v[172:175], v[50:53]
	v_mfma_f32_16x16x32_bf16 v[42:45], v[156:159], v[180:183], v[42:45]
	v_mfma_f32_16x16x32_bf16 v[34:37], v[164:167], v[180:183], v[34:37]
	v_mfma_f32_16x16x32_bf16 v[26:29], v[156:159], v[200:203], v[26:29]
	v_mfma_f32_16x16x32_bf16 v[18:21], v[164:167], v[200:203], v[18:21]
	v_mfma_f32_16x16x32_bf16 v[10:13], v[156:159], v[208:211], v[10:13]
	v_mfma_f32_16x16x32_bf16 v[2:5], v[164:167], v[208:211], v[2:5]
	v_mfma_f32_16x16x32_bf16 v[58:61], v[160:163], v[176:179], v[58:61]
	v_mfma_f32_16x16x32_bf16 v[50:53], v[168:171], v[176:179], v[50:53]
	v_mfma_f32_16x16x32_bf16 v[42:45], v[160:163], v[196:199], v[42:45]
	v_mfma_f32_16x16x32_bf16 v[34:37], v[168:171], v[196:199], v[34:37]
	v_mfma_f32_16x16x32_bf16 v[26:29], v[160:163], v[204:207], v[26:29]
	v_mfma_f32_16x16x32_bf16 v[18:21], v[168:171], v[204:207], v[18:21]
	v_mfma_f32_16x16x32_bf16 v[10:13], v[160:163], v[212:215], v[10:13]
	v_mfma_f32_16x16x32_bf16 v[2:5], v[168:171], v[212:215], v[2:5]
	s_barrier
	s_add_u32 s58, s58, 0x100
	s_addc_u32 s59, s59, 0
	s_cmp_ge_i32 s47, s81
	s_mov_b32 s6, s47
	s_cbranch_scc0 .LBB0_806
	s_and_b64 vcc, exec, s[10:11]
	s_cbranch_vccz .LBB0_809
	s_barrier
